# MFMA-VALU interleave rebalancing (lever 8): 8 of a step's 32 exps moved from the VALU-bound PV phase into the first four MFMA gaps of the next step's QK phase (steady loop, first->second copy transiti
# speedup vs baseline: 1.0009x; 1.0009x over previous
.LBB0_149:
	ds_read_b128 v[32:35], v180
	ds_read_b128 v[84:87], v180 offset:32
	ds_read_b128 v[136:139], v180 offset:128
	ds_read_b128 v[36:39], v180 offset:160
	ds_read_b128 v[88:91], v180 offset:64
	ds_read_b128 v[92:95], v180 offset:96
	ds_read_b128 v[40:43], v180 offset:192
	ds_read_b128 v[44:47], v180 offset:224
	s_waitcnt lgkmcnt(14)
	v_mfma_f32_32x32x16_bf16 v[16:31], v[124:127], v[164:167], v[16:31]
	v_exp_f32_e32 v64, v64
	v_exp_f32_e32 v65, v65
	v_exp_f32_e32 v66, v66
	v_exp_f32_e32 v67, v67
	s_waitcnt lgkmcnt(7)
	v_pk_add_f32 v[80:81], v[32:33], v[204:205] op_sel_hi:[1,0] neg_lo:[0,1] neg_hi:[0,1]
	v_pk_add_f32 v[82:83], v[34:35], v[204:205] op_sel_hi:[1,0] neg_lo:[0,1] neg_hi:[0,1]
	s_waitcnt lgkmcnt(2)
	v_mfma_f32_32x32x16_bf16 v[0:15], v[124:127], v[160:163], v[0:15]
	v_exp_f32_e32 v68, v68
	v_exp_f32_e32 v69, v69
	v_exp_f32_e32 v70, v70
	v_exp_f32_e32 v71, v71
	v_pk_add_f32 v[84:85], v[84:85], v[204:205] op_sel_hi:[1,0] neg_lo:[0,1] neg_hi:[0,1]
	v_pk_add_f32 v[86:87], v[86:87], v[204:205] op_sel_hi:[1,0] neg_lo:[0,1] neg_hi:[0,1]
	v_add_u32_e32 v124, s28, v220
	ds_read_b128 v[168:171], v124
	ds_read_b128 v[128:131], v124 offset:512
	v_mfma_f32_32x32x16_bf16 v[16:31], v[120:123], v[152:155], v[16:31]
	v_exp_f32_e32 v72, v72
	v_exp_f32_e32 v73, v73
	v_exp_f32_e32 v74, v74
	v_exp_f32_e32 v75, v75
	v_pk_add_f32 v[88:89], v[88:89], v[204:205] op_sel_hi:[1,0] neg_lo:[0,1] neg_hi:[0,1]
	v_pk_add_f32 v[90:91], v[90:91], v[204:205] op_sel_hi:[1,0] neg_lo:[0,1] neg_hi:[0,1]
	ds_read_b128 v[164:167], v124 offset:2048
	ds_read_b128 v[152:155], v124 offset:2560
	v_mfma_f32_32x32x16_bf16 v[0:15], v[120:123], v[148:151], v[0:15]
	v_exp_f32_e32 v76, v76
	v_exp_f32_e32 v77, v77
	v_exp_f32_e32 v78, v78
	v_exp_f32_e32 v79, v79
	v_pk_add_f32 v[92:93], v[92:93], v[204:205] op_sel_hi:[1,0] neg_lo:[0,1] neg_hi:[0,1]
	v_pk_add_f32 v[94:95], v[94:95], v[204:205] op_sel_hi:[1,0] neg_lo:[0,1] neg_hi:[0,1]
	ds_read_b128 v[160:163], v124 offset:4096
	ds_read_b128 v[148:151], v124 offset:4608
	v_mfma_f32_32x32x16_bf16 v[16:31], v[112:115], v[156:159], v[16:31]
	v_exp_f32_e32 v48, v48
	v_exp_f32_e32 v49, v49
	v_exp_f32_e32 v50, v50
	v_exp_f32_e32 v51, v51
	v_pk_add_f32 v[32:33], v[136:137], v[204:205] op_sel_hi:[1,0] neg_lo:[0,1] neg_hi:[0,1]
	v_pk_add_f32 v[34:35], v[138:139], v[204:205] op_sel_hi:[1,0] neg_lo:[0,1] neg_hi:[0,1]
	s_waitcnt lgkmcnt(6)
	ds_read_b128 v[156:159], v124 offset:6144
	ds_read_b128 v[136:139], v124 offset:6656
	v_mfma_f32_32x32x16_bf16 v[0:15], v[112:115], v[144:147], v[0:15]
	v_exp_f32_e32 v52, v52
	v_exp_f32_e32 v53, v53
	v_exp_f32_e32 v54, v54
	v_exp_f32_e32 v55, v55
	v_pk_add_f32 v[36:37], v[36:37], v[204:205] op_sel_hi:[1,0] neg_lo:[0,1] neg_hi:[0,1]
	v_pk_add_f32 v[38:39], v[38:39], v[204:205] op_sel_hi:[1,0] neg_lo:[0,1] neg_hi:[0,1]
	v_mfma_f32_32x32x16_bf16 v[16:31], v[104:107], v[140:143], v[16:31]
	v_pk_add_f32 v[40:41], v[40:41], v[204:205] op_sel_hi:[1,0] neg_lo:[0,1] neg_hi:[0,1]
	v_pk_add_f32 v[42:43], v[42:43], v[204:205] op_sel_hi:[1,0] neg_lo:[0,1] neg_hi:[0,1]
	v_mfma_f32_32x32x16_bf16 v[0:15], v[104:107], v[132:135], v[0:15]
	v_pk_add_f32 v[44:45], v[44:45], v[204:205] op_sel_hi:[1,0] neg_lo:[0,1] neg_hi:[0,1]
	v_pk_add_f32 v[46:47], v[46:47], v[204:205] op_sel_hi:[1,0] neg_lo:[0,1] neg_hi:[0,1]
	s_waitcnt vmcnt(2) lgkmcnt(0)
	s_barrier
	s_andn2_b64 vcc, exec, s[6:7]
	s_cbranch_vccnz .LBB0_151
	s_waitcnt lgkmcnt(0)
	ds_read_b128 v[132:135], v216 offset:49248
	ds_read_b128 v[140:143], v216 offset:49216
	ds_read_b128 v[144:147], v216 offset:49184
	ds_read_b128 v[172:175], v216 offset:49152
	s_waitcnt lgkmcnt(3)
	v_pk_mul_f32 v[30:31], v[30:31], v[134:135]
	s_waitcnt lgkmcnt(2)
	v_pk_mul_f32 v[26:27], v[26:27], v[142:143]
	s_waitcnt lgkmcnt(1)
	v_pk_mul_f32 v[22:23], v[22:23], v[146:147]
	s_waitcnt lgkmcnt(0)
	v_pk_mul_f32 v[18:19], v[18:19], v[174:175]
	v_pk_mul_f32 v[28:29], v[28:29], v[132:133]
	v_pk_mul_f32 v[24:25], v[24:25], v[140:141]
	v_pk_mul_f32 v[20:21], v[20:21], v[144:145]
	v_pk_mul_f32 v[16:17], v[16:17], v[172:173]
	v_pk_mul_f32 v[14:15], v[14:15], v[134:135]
	v_pk_mul_f32 v[10:11], v[10:11], v[142:143]
	v_pk_mul_f32 v[6:7], v[6:7], v[146:147]
	v_pk_mul_f32 v[2:3], v[2:3], v[174:175]
	v_pk_mul_f32 v[12:13], v[12:13], v[132:133]
	v_pk_mul_f32 v[8:9], v[8:9], v[140:141]
	v_pk_mul_f32 v[4:5], v[4:5], v[144:145]
	v_pk_mul_f32 v[0:1], v[0:1], v[172:173]
.LBB0_151:
	s_add_i32 s6, s28, 0x2000
	s_cmpk_lg_i32 s28, 0x4000
	s_cselect_b32 s22, s6, 0
	v_add_u32_e32 v182, s41, v221
	ds_read_b64_tr_b16 v[144:145], v182 offset:24576
	ds_read_b64_tr_b16 v[146:147], v182 offset:25088
	v_mfma_f32_32x32x16_bf16 v[80:95], v[168:171], v[116:119], v[80:95]
	v_exp_f32_e32 v56, v56
	v_exp_f32_e32 v57, v57
	v_add_f32_e32 v104, v64, v65
	v_add_f32_e32 v104, v66, v104
	v_add_f32_e32 v104, v67, v104
	v_add_f32_e32 v104, v68, v104
	v_add_f32_e32 v104, v69, v104
	v_cvt_pk_bf16_f32 v124, v64, v65
	v_cvt_pk_bf16_f32 v125, v66, v67
	ds_read_b64_tr_b16 v[140:141], v182 offset:28672
	ds_read_b64_tr_b16 v[142:143], v182 offset:29184
	v_mfma_f32_32x32x16_bf16 v[32:47], v[128:131], v[116:119], v[32:47]
	v_exp_f32_e32 v58, v58
	v_exp_f32_e32 v59, v59
	v_add_f32_e32 v64, v70, v104
	v_add_f32_e32 v64, v71, v64
	v_add_f32_e32 v64, v72, v64
	v_add_f32_e32 v64, v73, v64
	v_cvt_pk_bf16_f32 v126, v68, v69
	v_cvt_pk_bf16_f32 v127, v70, v71
	ds_read_b64_tr_b16 v[132:133], v182 offset:25600
	ds_read_b64_tr_b16 v[134:135], v182 offset:26112
	v_mfma_f32_32x32x16_bf16 v[80:95], v[164:167], v[108:111], v[80:95]
	v_exp_f32_e32 v60, v60
	v_exp_f32_e32 v61, v61
	v_add_f32_e32 v64, v74, v64
	v_add_f32_e32 v64, v75, v64
	v_add_f32_e32 v64, v76, v64
	v_add_f32_e32 v64, v77, v64
	v_cvt_pk_bf16_f32 v120, v72, v73
	v_cvt_pk_bf16_f32 v121, v74, v75
	ds_read_b64_tr_b16 v[128:129], v182 offset:29696
	ds_read_b64_tr_b16 v[130:131], v182 offset:30208
	v_mfma_f32_32x32x16_bf16 v[32:47], v[152:155], v[108:111], v[32:47]
	v_exp_f32_e32 v62, v62
	v_exp_f32_e32 v63, v63
	v_add_f32_e32 v64, v78, v64
	v_add_f32_e32 v64, v79, v64
	v_add_f32_e32 v64, v48, v64
	v_add_f32_e32 v64, v49, v64
	v_cvt_pk_bf16_f32 v122, v76, v77
	v_cvt_pk_bf16_f32 v123, v78, v79
	ds_read_b64_tr_b16 v[172:173], v182 offset:26624
	ds_read_b64_tr_b16 v[174:175], v182 offset:27136
	v_mfma_f32_32x32x16_bf16 v[80:95], v[160:163], v[100:103], v[80:95]
	v_add_f32_e32 v64, v50, v64
	v_add_f32_e32 v64, v51, v64
	v_add_f32_e32 v64, v52, v64
	v_add_f32_e32 v64, v53, v64
	v_cvt_pk_bf16_f32 v112, v48, v49
	v_cvt_pk_bf16_f32 v113, v50, v51
	ds_read_b64_tr_b16 v[168:169], v182 offset:30720
	ds_read_b64_tr_b16 v[170:171], v182 offset:31232
	v_mfma_f32_32x32x16_bf16 v[32:47], v[148:151], v[100:103], v[32:47]
	v_add_f32_e32 v48, v54, v64
	v_add_f32_e32 v48, v55, v48
	v_add_f32_e32 v48, v56, v48
	v_add_f32_e32 v48, v57, v48
	v_cvt_pk_bf16_f32 v114, v52, v53
	v_cvt_pk_bf16_f32 v115, v54, v55
	ds_read_b64_tr_b16 v[164:165], v182 offset:27648
	ds_read_b64_tr_b16 v[166:167], v182 offset:28160
	v_mfma_f32_32x32x16_bf16 v[80:95], v[156:159], v[96:99], v[80:95]
	v_add_f32_e32 v48, v58, v48
	v_add_f32_e32 v48, v59, v48
	v_add_f32_e32 v48, v60, v48
	v_add_f32_e32 v48, v61, v48
	v_cvt_pk_bf16_f32 v104, v56, v57
	v_cvt_pk_bf16_f32 v105, v58, v59
	ds_read_b64_tr_b16 v[160:161], v182 offset:31744
	ds_read_b64_tr_b16 v[162:163], v182 offset:32256
	v_mfma_f32_32x32x16_bf16 v[32:47], v[136:139], v[96:99], v[32:47]
	v_add_f32_e32 v48, v62, v48
	v_add_f32_e32 v48, v63, v48
	v_add_f32_e32 v48, 0, v48
	v_cvt_pk_bf16_f32 v106, v60, v61
	v_cvt_pk_bf16_f32 v107, v62, v63
	v_max_f32_e32 v49, v80, v81
	s_nop 3
	v_max3_f32 v50, v82, v83, v33
	v_max3_f32 v49, v49, v32, v34
	v_max3_f32 v49, v49, v35, v84
	v_max3_f32 v50, v50, v86, v87
	v_max3_f32 v49, v49, v85, v36
	v_max3_f32 v50, v50, v38, v39
	v_max3_f32 v49, v49, v37, v88
	v_max3_f32 v50, v50, v90, v91
	v_max3_f32 v49, v49, v89, v40
	v_max3_f32 v50, v50, v42, v43
	v_max3_f32 v49, v49, v41, v92
	v_max3_f32 v50, v50, v94, v95
	v_max3_f32 v49, v49, v93, v44
	v_max3_f32 v50, v50, v46, v47
	v_add_f32_e32 v222, v181, v48
	v_max3_f32 v48, v49, v45, v50
	v_mov_b32_e32 v49, v48
	s_nop 1
	v_permlane32_swap_b32_e32 v48, v49
	v_max_f32_e32 v49, v49, v49
	v_max_f32_e32 v48, v48, v48
	s_add_i32 s6, s28, s18
	s_mov_b32 m0, s6
	s_nop 0
	global_load_lds_dwordx4 v[178:179], off
	v_max_f32_e32 v48, v48, v49
	s_add_i32 s6, s22, s19
	s_mov_b32 m0, s6
	s_nop 0
	global_load_lds_dwordx4 v[176:177], off
	v_cmp_lt_f32_e32 vcc, s47, v48
	s_cmp_lg_u64 vcc, 0
	s_cselect_b64 s[6:7], -1, 0
	s_cbranch_vccnz .LBB0_159
